# adds: P6: half of the workgroups (bit 3 of the workgroup index) run their split-K sample tile before their GEMM unit, so the L2/MALL-bound tiles overlap the other half's MFMA-bound K loops
# speedup vs baseline: 1.0004x; 1.0004x over previous
.LBB0_1101:
	s_cmp_lg_u32 s90, 0x100
	s_cbranch_scc1 .Lp6_main
	s_bitcmp1_b32 s14, 3
	s_cbranch_scc0 .Lp6_main
	s_mov_b32 s32, s14
	s_cmp_lg_u32 s90, 0x100
	s_cbranch_scc1 .Lp6_tilemap_doneB
	s_and_b32 s32, s14, 1
	s_lshl_b32 s32, s32, 2
	s_bfe_u32 s7, s14, 0x20003
	s_or_b32 s32, s32, s7
	s_lshl_b32 s32, s32, 5
	s_bfe_u32 s7, s14, 0x20001
	s_lshl_b32 s7, s7, 3
	s_or_b32 s32, s32, s7
	s_lshr_b32 s7, s14, 5
	s_or_b32 s32, s32, s7
.Lp6_tilemap_doneB:
	s_branch .Lp6_small_body

.Lp6_tilemap_doneA:
	s_cmp_lg_u32 s90, 0x100
	s_cbranch_scc1 .Lp6_small_checks
	s_bitcmp1_b32 s14, 3
	s_cbranch_scc1 .LBB0_1186

.Lp6_small_body:
	s_mul_i32 s0, s17, 0x160
	s_mov_b32 s1, 0
	s_lshl_b64 s[2:3], s[0:1], 1
	s_add_u32 s4, s18, s2
	s_addc_u32 s5, s19, s3
	s_add_u32 s2, s24, s2
	s_addc_u32 s3, s25, s3
	s_lshl_b32 s0, s17, 13
	v_lshlrev_b32_e32 v2, 4, v168
	v_mov_b32_e32 v3, 0
	s_add_i32 s0, s0, 0
	v_lshl_add_u64 v[4:5], s[4:5], 0, v[2:3]
	v_lshl_add_u64 v[6:7], s[2:3], 0, v[2:3]
	v_add_u32_e32 v9, s0, v2
	v_and_b32_e32 v2, 0x7e0, v171
	v_lshlrev_b32_e32 v10, 2, v2
	v_and_b32_e32 v2, 28, v171
	v_lshlrev_b32_e32 v8, 7, v1
	v_lshlrev_b32_e32 v11, 2, v2
	v_add3_u32 v18, 0, v10, v11
	s_lshl_b32 s2, s32, 1
	s_lshl_b32 s3, s90, 1
	s_lshl_b32 s4, s32, 5
	s_lshl_b32 s5, s90, 5
	s_movk_i32 s6, 0x1600
	v_add_u32_e32 v19, v9, v8
	v_lshlrev_b32_e32 v8, 1, v2
	v_mov_b32_e32 v9, v3
.LBB0_1185:
	s_and_b32 s7, s2, 0xffffffc0
	s_addk_i32 s7, 0x4000
	v_or_b32_e32 v10, s7, v1
	v_mad_i64_i32 v[12:13], s[26:27], v10, s6, v[4:5]
	v_add_co_u32_e32 v14, vcc, 0x16000, v12
	s_and_b32 s0, s4, 0x3e0
	s_nop 0
	v_addc_co_u32_e32 v15, vcc, 0, v13, vcc
	v_or_b32_e32 v2, s0, v1
	v_add_co_u32_e32 v16, vcc, 0x2c000, v12
	v_mul_u32_u24_e32 v2, 0xb00, v2
	s_nop 0
	v_addc_co_u32_e32 v17, vcc, 0, v13, vcc
	v_lshlrev_b32_e32 v2, 1, v2
	v_add_co_u32_e32 v100, vcc, 0x42000, v12
	v_lshl_add_u64 v[10:11], v[6:7], 0, v[2:3]
	s_nop 0
	v_addc_co_u32_e32 v101, vcc, 0, v13, vcc
	v_add_co_u32_e32 v102, vcc, 0x16000, v10
	v_addc_co_u32_e32 v103, vcc, 0, v11, vcc
	v_mov_b64_e32 v[232:233], v[102:103]
	v_mov_b64_e32 v[234:235], v[100:101]
	global_load_dwordx4 v[20:23], v[10:11], off
	global_load_dwordx4 v[24:27], v[232:233], off
	global_load_dwordx4 v[28:31], v[12:13], off
	global_load_dwordx4 v[32:35], v[14:15], off
	global_load_dwordx4 v[36:39], v[16:17], off
	global_load_dwordx4 v[40:43], v[234:235], off
	global_load_dwordx4 v[44:47], v[10:11], off offset:64
	global_load_dwordx4 v[48:51], v[232:233], off offset:64
	global_load_dwordx4 v[52:55], v[12:13], off offset:64
	global_load_dwordx4 v[56:59], v[14:15], off offset:64
	global_load_dwordx4 v[60:63], v[16:17], off offset:64
	global_load_dwordx4 v[64:67], v[234:235], off offset:64
	global_load_dwordx4 v[68:71], v[10:11], off offset:128
	global_load_dwordx4 v[72:75], v[232:233], off offset:128
	global_load_dwordx4 v[76:79], v[12:13], off offset:128
	global_load_dwordx4 v[80:83], v[14:15], off offset:128
	global_load_dwordx4 v[84:87], v[16:17], off offset:128
	global_load_dwordx4 v[88:91], v[234:235], off offset:128
	global_load_dwordx4 v[92:95], v[10:11], off offset:192
	global_load_dwordx4 v[96:99], v[232:233], off offset:192
	global_load_dwordx4 v[100:103], v[12:13], off offset:192
	global_load_dwordx4 v[104:107], v[14:15], off offset:192
	global_load_dwordx4 v[108:111], v[16:17], off offset:192
	global_load_dwordx4 v[112:115], v[234:235], off offset:192
	global_load_dwordx4 v[184:187], v[10:11], off offset:256
	global_load_dwordx4 v[188:191], v[232:233], off offset:256
	global_load_dwordx4 v[192:195], v[12:13], off offset:256
	global_load_dwordx4 v[196:199], v[14:15], off offset:256
	global_load_dwordx4 v[200:203], v[16:17], off offset:256
	global_load_dwordx4 v[204:207], v[234:235], off offset:256
	global_load_dwordx4 v[208:211], v[10:11], off offset:320
	global_load_dwordx4 v[212:215], v[232:233], off offset:320
	global_load_dwordx4 v[216:219], v[12:13], off offset:320
	global_load_dwordx4 v[220:223], v[14:15], off offset:320
	global_load_dwordx4 v[224:227], v[16:17], off offset:320
	global_load_dwordx4 v[228:231], v[234:235], off offset:320
	s_lshl_b32 s0, s0, 1
	s_add_i32 s14, s14, s90
	s_add_i32 s2, s2, s3
	s_add_i32 s4, s4, s5
	s_cmpk_gt_i32 s14, 0xff
	s_waitcnt vmcnt(30)
	v_mfma_f32_16x16x32_bf16 v[116:119], v[20:23], v[28:31], 0
	v_mfma_f32_16x16x32_bf16 v[120:123], v[20:23], v[32:35], 0
	v_mfma_f32_16x16x32_bf16 v[124:127], v[20:23], v[36:39], 0
	v_mfma_f32_16x16x32_bf16 v[128:131], v[20:23], v[40:43], 0
	v_mfma_f32_16x16x32_bf16 v[132:135], v[24:27], v[28:31], 0
	v_mfma_f32_16x16x32_bf16 v[136:139], v[24:27], v[32:35], 0
	v_mfma_f32_16x16x32_bf16 v[140:143], v[24:27], v[36:39], 0
	v_mfma_f32_16x16x32_bf16 v[144:147], v[24:27], v[40:43], 0
	s_waitcnt vmcnt(24)
	v_mfma_f32_16x16x32_bf16 v[116:119], v[44:47], v[52:55], v[116:119]
	v_mfma_f32_16x16x32_bf16 v[120:123], v[44:47], v[56:59], v[120:123]
	v_mfma_f32_16x16x32_bf16 v[124:127], v[44:47], v[60:63], v[124:127]
	v_mfma_f32_16x16x32_bf16 v[128:131], v[44:47], v[64:67], v[128:131]
	v_mfma_f32_16x16x32_bf16 v[132:135], v[48:51], v[52:55], v[132:135]
	v_mfma_f32_16x16x32_bf16 v[136:139], v[48:51], v[56:59], v[136:139]
	v_mfma_f32_16x16x32_bf16 v[140:143], v[48:51], v[60:63], v[140:143]
	v_mfma_f32_16x16x32_bf16 v[144:147], v[48:51], v[64:67], v[144:147]
	s_waitcnt vmcnt(18)
	v_mfma_f32_16x16x32_bf16 v[116:119], v[68:71], v[76:79], v[116:119]
	v_mfma_f32_16x16x32_bf16 v[120:123], v[68:71], v[80:83], v[120:123]
	v_mfma_f32_16x16x32_bf16 v[124:127], v[68:71], v[84:87], v[124:127]
	v_mfma_f32_16x16x32_bf16 v[128:131], v[68:71], v[88:91], v[128:131]
	v_mfma_f32_16x16x32_bf16 v[132:135], v[72:75], v[76:79], v[132:135]
	v_mfma_f32_16x16x32_bf16 v[136:139], v[72:75], v[80:83], v[136:139]
	v_mfma_f32_16x16x32_bf16 v[140:143], v[72:75], v[84:87], v[140:143]
	v_mfma_f32_16x16x32_bf16 v[144:147], v[72:75], v[88:91], v[144:147]
	s_waitcnt vmcnt(12)
	v_mfma_f32_16x16x32_bf16 v[116:119], v[92:95], v[100:103], v[116:119]
	v_mfma_f32_16x16x32_bf16 v[120:123], v[92:95], v[104:107], v[120:123]
	v_mfma_f32_16x16x32_bf16 v[124:127], v[92:95], v[108:111], v[124:127]
	v_mfma_f32_16x16x32_bf16 v[128:131], v[92:95], v[112:115], v[128:131]
	v_mfma_f32_16x16x32_bf16 v[132:135], v[96:99], v[100:103], v[132:135]
	v_mfma_f32_16x16x32_bf16 v[136:139], v[96:99], v[104:107], v[136:139]
	v_mfma_f32_16x16x32_bf16 v[140:143], v[96:99], v[108:111], v[140:143]
	v_mfma_f32_16x16x32_bf16 v[144:147], v[96:99], v[112:115], v[144:147]
	global_load_dwordx4 v[20:23], v[10:11], off offset:384
	global_load_dwordx4 v[24:27], v[232:233], off offset:384
	global_load_dwordx4 v[28:31], v[12:13], off offset:384
	global_load_dwordx4 v[32:35], v[14:15], off offset:384
	global_load_dwordx4 v[36:39], v[16:17], off offset:384
	global_load_dwordx4 v[40:43], v[234:235], off offset:384
	global_load_dwordx4 v[44:47], v[10:11], off offset:448
	global_load_dwordx4 v[48:51], v[232:233], off offset:448
	global_load_dwordx4 v[52:55], v[12:13], off offset:448
	global_load_dwordx4 v[56:59], v[14:15], off offset:448
	global_load_dwordx4 v[60:63], v[16:17], off offset:448
	global_load_dwordx4 v[64:67], v[234:235], off offset:448
	global_load_dwordx4 v[68:71], v[10:11], off offset:512
	global_load_dwordx4 v[72:75], v[232:233], off offset:512
	global_load_dwordx4 v[76:79], v[12:13], off offset:512
	global_load_dwordx4 v[80:83], v[14:15], off offset:512
	global_load_dwordx4 v[84:87], v[16:17], off offset:512
	global_load_dwordx4 v[88:91], v[234:235], off offset:512
	global_load_dwordx4 v[92:95], v[10:11], off offset:576
	global_load_dwordx4 v[96:99], v[232:233], off offset:576
	global_load_dwordx4 v[100:103], v[12:13], off offset:576
	global_load_dwordx4 v[104:107], v[14:15], off offset:576
	global_load_dwordx4 v[108:111], v[16:17], off offset:576
	global_load_dwordx4 v[112:115], v[234:235], off offset:576
	s_waitcnt vmcnt(30)
	v_mfma_f32_16x16x32_bf16 v[116:119], v[184:187], v[192:195], v[116:119]
	v_mfma_f32_16x16x32_bf16 v[120:123], v[184:187], v[196:199], v[120:123]
	v_mfma_f32_16x16x32_bf16 v[124:127], v[184:187], v[200:203], v[124:127]
	v_mfma_f32_16x16x32_bf16 v[128:131], v[184:187], v[204:207], v[128:131]
	v_mfma_f32_16x16x32_bf16 v[132:135], v[188:191], v[192:195], v[132:135]
	v_mfma_f32_16x16x32_bf16 v[136:139], v[188:191], v[196:199], v[136:139]
	v_mfma_f32_16x16x32_bf16 v[140:143], v[188:191], v[200:203], v[140:143]
	v_mfma_f32_16x16x32_bf16 v[144:147], v[188:191], v[204:207], v[144:147]
	s_waitcnt vmcnt(24)
	v_mfma_f32_16x16x32_bf16 v[116:119], v[208:211], v[216:219], v[116:119]
	v_mfma_f32_16x16x32_bf16 v[120:123], v[208:211], v[220:223], v[120:123]
	v_mfma_f32_16x16x32_bf16 v[124:127], v[208:211], v[224:227], v[124:127]
	v_mfma_f32_16x16x32_bf16 v[128:131], v[208:211], v[228:231], v[128:131]
	v_mfma_f32_16x16x32_bf16 v[132:135], v[212:215], v[216:219], v[132:135]
	v_mfma_f32_16x16x32_bf16 v[136:139], v[212:215], v[220:223], v[136:139]
	v_mfma_f32_16x16x32_bf16 v[140:143], v[212:215], v[224:227], v[140:143]
	v_mfma_f32_16x16x32_bf16 v[144:147], v[212:215], v[228:231], v[144:147]
	global_load_dwordx4 v[184:187], v[10:11], off offset:640
	global_load_dwordx4 v[188:191], v[232:233], off offset:640
	global_load_dwordx4 v[192:195], v[12:13], off offset:640
	global_load_dwordx4 v[196:199], v[14:15], off offset:640
	global_load_dwordx4 v[200:203], v[16:17], off offset:640
	global_load_dwordx4 v[204:207], v[234:235], off offset:640
	s_waitcnt vmcnt(24)
	v_mfma_f32_16x16x32_bf16 v[116:119], v[20:23], v[28:31], v[116:119]
	v_mfma_f32_16x16x32_bf16 v[120:123], v[20:23], v[32:35], v[120:123]
	v_mfma_f32_16x16x32_bf16 v[124:127], v[20:23], v[36:39], v[124:127]
	v_mfma_f32_16x16x32_bf16 v[128:131], v[20:23], v[40:43], v[128:131]
	v_mfma_f32_16x16x32_bf16 v[132:135], v[24:27], v[28:31], v[132:135]
	v_mfma_f32_16x16x32_bf16 v[136:139], v[24:27], v[32:35], v[136:139]
	v_mfma_f32_16x16x32_bf16 v[140:143], v[24:27], v[36:39], v[140:143]
	v_mfma_f32_16x16x32_bf16 v[144:147], v[24:27], v[40:43], v[144:147]
	s_waitcnt vmcnt(18)
	v_mfma_f32_16x16x32_bf16 v[116:119], v[44:47], v[52:55], v[116:119]
	v_mfma_f32_16x16x32_bf16 v[120:123], v[44:47], v[56:59], v[120:123]
	v_mfma_f32_16x16x32_bf16 v[124:127], v[44:47], v[60:63], v[124:127]
	v_mfma_f32_16x16x32_bf16 v[128:131], v[44:47], v[64:67], v[128:131]
	v_mfma_f32_16x16x32_bf16 v[132:135], v[48:51], v[52:55], v[132:135]
	v_mfma_f32_16x16x32_bf16 v[136:139], v[48:51], v[56:59], v[136:139]
	v_mfma_f32_16x16x32_bf16 v[140:143], v[48:51], v[60:63], v[140:143]
	v_mfma_f32_16x16x32_bf16 v[144:147], v[48:51], v[64:67], v[144:147]
	s_waitcnt vmcnt(12)
	v_mfma_f32_16x16x32_bf16 v[116:119], v[68:71], v[76:79], v[116:119]
	v_mfma_f32_16x16x32_bf16 v[120:123], v[68:71], v[80:83], v[120:123]
	v_mfma_f32_16x16x32_bf16 v[124:127], v[68:71], v[84:87], v[124:127]
	v_mfma_f32_16x16x32_bf16 v[128:131], v[68:71], v[88:91], v[128:131]
	v_mfma_f32_16x16x32_bf16 v[132:135], v[72:75], v[76:79], v[132:135]
	v_mfma_f32_16x16x32_bf16 v[136:139], v[72:75], v[80:83], v[136:139]
	v_mfma_f32_16x16x32_bf16 v[140:143], v[72:75], v[84:87], v[140:143]
	v_mfma_f32_16x16x32_bf16 v[144:147], v[72:75], v[88:91], v[144:147]
	s_waitcnt vmcnt(6)
	v_mfma_f32_16x16x32_bf16 v[116:119], v[92:95], v[100:103], v[116:119]
	v_mfma_f32_16x16x32_bf16 v[120:123], v[92:95], v[104:107], v[120:123]
	v_mfma_f32_16x16x32_bf16 v[124:127], v[92:95], v[108:111], v[124:127]
	v_mfma_f32_16x16x32_bf16 v[128:131], v[92:95], v[112:115], v[128:131]
	v_mfma_f32_16x16x32_bf16 v[132:135], v[96:99], v[100:103], v[132:135]
	v_mfma_f32_16x16x32_bf16 v[136:139], v[96:99], v[104:107], v[136:139]
	v_mfma_f32_16x16x32_bf16 v[140:143], v[96:99], v[108:111], v[140:143]
	v_mfma_f32_16x16x32_bf16 v[144:147], v[96:99], v[112:115], v[144:147]
	s_waitcnt vmcnt(0)
	v_mfma_f32_16x16x32_bf16 v[116:119], v[184:187], v[192:195], v[116:119]
	v_mfma_f32_16x16x32_bf16 v[120:123], v[184:187], v[196:199], v[120:123]
	v_mfma_f32_16x16x32_bf16 v[124:127], v[184:187], v[200:203], v[124:127]
	v_mfma_f32_16x16x32_bf16 v[128:131], v[184:187], v[204:207], v[128:131]
	v_mfma_f32_16x16x32_bf16 v[132:135], v[188:191], v[192:195], v[132:135]
	v_mfma_f32_16x16x32_bf16 v[136:139], v[188:191], v[196:199], v[136:139]
	v_mfma_f32_16x16x32_bf16 v[140:143], v[188:191], v[200:203], v[140:143]
	v_mfma_f32_16x16x32_bf16 v[144:147], v[188:191], v[204:207], v[144:147]
	v_or_b32_e32 v236, s7, v170
	v_ashrrev_i32_e32 v237, 31, v236
	v_lshlrev_b64 v[236:237], 11, v[236:237]
	v_lshl_add_u64 v[236:237], s[8:9], 0, v[236:237]
	v_lshl_add_u64 v[236:237], v[236:237], 0, s[0:1]
	v_lshl_add_u64 v[56:57], v[236:237], 0, v[8:9]
	s_waitcnt lgkmcnt(0)
	s_barrier
	s_nop 7
	s_nop 7
	ds_write_b128 v19, v[116:119]
	ds_write_b128 v19, v[120:123] offset:2048
	ds_write_b128 v19, v[124:127] offset:4096
	ds_write_b128 v19, v[128:131] offset:6144
	ds_write_b128 v19, v[132:135] offset:64
	ds_write_b128 v19, v[136:139] offset:2112
	ds_write_b128 v19, v[140:143] offset:4160
	ds_write_b128 v19, v[144:147] offset:6208
	s_waitcnt lgkmcnt(0)
	s_barrier
	global_load_dwordx2 v[44:45], v[56:57], off
	ds_read_b128 v[10:13], v18
	ds_read_b128 v[14:17], v18 offset:8192
	ds_read_b128 v[20:23], v18 offset:16384
	ds_read_b128 v[24:27], v18 offset:24576
	ds_read_b128 v[28:31], v18 offset:32768
	ds_read_b128 v[32:35], v18 offset:40960
	ds_read_b128 v[36:39], v18 offset:49152
	ds_read_b128 v[40:43], v18 offset:57344
	s_waitcnt lgkmcnt(7)
	v_pk_add_f32 v[12:13], v[12:13], 0 op_sel_hi:[1,0]
	v_pk_add_f32 v[10:11], v[10:11], 0 op_sel_hi:[1,0]
	s_waitcnt lgkmcnt(6)
	v_pk_add_f32 v[12:13], v[12:13], v[16:17]
	v_pk_add_f32 v[10:11], v[10:11], v[14:15]
	s_waitcnt lgkmcnt(5)
	v_pk_add_f32 v[12:13], v[12:13], v[22:23]
	v_pk_add_f32 v[10:11], v[10:11], v[20:21]
	s_waitcnt lgkmcnt(4)
	v_pk_add_f32 v[12:13], v[12:13], v[26:27]
	v_pk_add_f32 v[10:11], v[10:11], v[24:25]
	s_waitcnt lgkmcnt(3)
	v_pk_add_f32 v[12:13], v[12:13], v[30:31]
	v_pk_add_f32 v[10:11], v[10:11], v[28:29]
	s_waitcnt lgkmcnt(2)
	v_pk_add_f32 v[12:13], v[12:13], v[34:35]
	v_pk_add_f32 v[10:11], v[10:11], v[32:33]
	s_waitcnt lgkmcnt(1)
	v_pk_add_f32 v[12:13], v[12:13], v[38:39]
	v_pk_add_f32 v[10:11], v[10:11], v[36:37]
	s_waitcnt lgkmcnt(0)
	v_pk_add_f32 v[12:13], v[12:13], v[42:43]
	v_pk_add_f32 v[10:11], v[10:11], v[40:41]
	s_waitcnt vmcnt(0)
	v_lshlrev_b32_e32 v2, 16, v44
	v_and_b32_e32 v14, 0xffff0000, v44
	v_lshlrev_b32_e32 v15, 16, v45
	v_and_b32_e32 v16, 0xffff0000, v45
	v_add_f32_e32 v2, v10, v2
	v_add_f32_e32 v10, v11, v14
	v_add_f32_e32 v11, v12, v15
	v_add_f32_e32 v12, v13, v16
	v_cvt_pk_bf16_f32 v10, v2, v10
	v_cvt_pk_bf16_f32 v11, v11, v12
	global_store_dwordx2 v[56:57], v[10:11], off sc1
	s_cbranch_scc0 .LBB0_1185
	s_cmp_lg_u32 s90, 0x100
	s_cbranch_scc1 .LBB0_1186
	s_bitcmp1_b32 s14, 3
	s_cbranch_scc0 .LBB0_1186
	s_sub_i32 s14, s14, s90
	s_waitcnt lgkmcnt(0)
	s_barrier
	s_branch .Lp6_main
